# in-loop residual fold with full-line loads: lanes fr / fr^8 fetch whole 128-byte lines (rows 0-7 / 8-15) and the fold uses v_add_f32_dpp row_ror:8 under bank masks (half the cache-line requests of the
# speedup vs baseline: 1.5560x; 1.0107x over previous
.Lrk_344:
	s_add_i32 vcc_lo, s50, 2
	s_add_u32 s68, s48, 0x80
	s_addc_u32 s51, s49, 0
	s_add_i32 s70, 0, 0x10000
	s_cmp_eq_u32 s15, s50
	s_cselect_b32 s51, s1, s51
	s_cselect_b32 s50, s0, s68
	v_add_u32_e32 v0, s70, v223
	s_cselect_b32 s69, s53, s57
	s_cselect_b32 s68, s52, s56
	s_add_i32 s71, 0, 0x14000
	ds_read_b128 v[130:133], v0
	ds_read_b128 v[134:137], v0 offset:1024
	ds_read_b128 v[138:141], v0 offset:2048
	ds_read_b128 v[142:145], v0 offset:3072
	v_add_u32_e32 v0, s71, v223
	ds_read_b128 v[146:149], v0
	ds_read_b128 v[150:153], v0 offset:1024
	ds_read_b128 v[154:157], v0 offset:2048
	ds_read_b128 v[158:161], v0 offset:3072
	s_add_i32 s98, vcc_lo, -2
	s_and_b32 s99, s98, 2
	s_lshl_b32 s99, s99, 8
	s_lshr_b32 vcc_hi, s98, 2
	s_and_b32 vcc_hi, vcc_hi, 3
	s_lshl_b32 vcc_hi, vcc_hi, 17
	s_or_b32 s99, s99, vcc_hi
	s_lshr_b32 vcc_hi, s98, 4
	s_lshl_b32 vcc_hi, vcc_hi, 20
	s_or_b32 s98, s99, vcc_hi
	s_add_u32 s98, s100, s98
	s_addc_u32 s99, s101, 0
	s_nop 0
	global_load_dwordx4 v[240:243], v238, s[98:99]
	v_lshl_add_u64 v[212:213], s[48:49], 0, v[192:193]
	s_add_i32 m0, s67, 0xc000
	ds_read_b128 v[162:165], v226
	ds_read_b128 v[166:169], v226 offset:1024
	ds_read_b128 v[170:173], v226 offset:2048
	ds_read_b128 v[174:177], v226 offset:3072
	ds_read_b128 v[196:199], v226 offset:4096
	ds_read_b128 v[200:203], v226 offset:5120
	ds_read_b128 v[204:207], v226 offset:6144
	ds_read_b128 v[208:211], v226 offset:7168
	global_load_lds_dwordx4 v[212:213], off
	v_lshl_add_u64 v[212:213], s[48:49], 0, v[194:195]
	s_add_i32 m0, s67, 0xe000
	s_nop 0
	global_load_lds_dwordx4 v[212:213], off
	s_waitcnt vmcnt(9)
	s_waitcnt lgkmcnt(0)
	s_barrier
	s_setprio 1
	s_waitcnt lgkmcnt(0)
	v_mfma_f32_16x16x32_bf16 v[126:129], v[130:133], v[162:165], v[126:129]
	v_mfma_f32_16x16x32_bf16 v[122:125], v[138:141], v[162:165], v[122:125]
	v_mfma_f32_16x16x32_bf16 v[118:121], v[130:133], v[170:173], v[118:121]
	v_mfma_f32_16x16x32_bf16 v[114:117], v[138:141], v[170:173], v[114:117]
	v_mfma_f32_16x16x32_bf16 v[102:105], v[130:133], v[196:199], v[102:105]
	v_mfma_f32_16x16x32_bf16 v[98:101], v[138:141], v[196:199], v[98:101]
	v_mfma_f32_16x16x32_bf16 v[86:89], v[130:133], v[204:207], v[86:89]
	v_mfma_f32_16x16x32_bf16 v[82:85], v[138:141], v[204:207], v[82:85]
	v_mfma_f32_16x16x32_bf16 v[126:129], v[134:137], v[166:169], v[126:129]
	v_mfma_f32_16x16x32_bf16 v[122:125], v[142:145], v[166:169], v[122:125]
	v_mfma_f32_16x16x32_bf16 v[118:121], v[134:137], v[174:177], v[118:121]
	v_mfma_f32_16x16x32_bf16 v[114:117], v[142:145], v[174:177], v[114:117]
	v_mfma_f32_16x16x32_bf16 v[102:105], v[134:137], v[200:203], v[102:105]
	v_mfma_f32_16x16x32_bf16 v[98:101], v[142:145], v[200:203], v[98:101]
	v_mfma_f32_16x16x32_bf16 v[86:89], v[134:137], v[208:211], v[86:89]
	v_mfma_f32_16x16x32_bf16 v[82:85], v[142:145], v[208:211], v[82:85]
	s_setprio 0
	s_setprio 1
	v_mfma_f32_16x16x32_bf16 v[110:113], v[146:149], v[162:165], v[110:113]
	v_mfma_f32_16x16x32_bf16 v[106:109], v[154:157], v[162:165], v[106:109]
	v_mfma_f32_16x16x32_bf16 v[94:97], v[146:149], v[170:173], v[94:97]
	v_mfma_f32_16x16x32_bf16 v[90:93], v[154:157], v[170:173], v[90:93]
	v_mfma_f32_16x16x32_bf16 v[78:81], v[146:149], v[196:199], v[78:81]
	v_mfma_f32_16x16x32_bf16 v[74:77], v[154:157], v[196:199], v[74:77]
	v_mfma_f32_16x16x32_bf16 v[70:73], v[146:149], v[204:207], v[70:73]
	v_mfma_f32_16x16x32_bf16 v[66:69], v[154:157], v[204:207], v[66:69]
	v_mfma_f32_16x16x32_bf16 v[110:113], v[150:153], v[166:169], v[110:113]
	v_mfma_f32_16x16x32_bf16 v[106:109], v[158:161], v[166:169], v[106:109]
	v_mfma_f32_16x16x32_bf16 v[94:97], v[150:153], v[174:177], v[94:97]
	v_mfma_f32_16x16x32_bf16 v[90:93], v[158:161], v[174:177], v[90:93]
	v_mfma_f32_16x16x32_bf16 v[78:81], v[150:153], v[200:203], v[78:81]
	v_mfma_f32_16x16x32_bf16 v[74:77], v[158:161], v[200:203], v[74:77]
	v_mfma_f32_16x16x32_bf16 v[70:73], v[150:153], v[208:211], v[70:73]
	v_mfma_f32_16x16x32_bf16 v[66:69], v[158:161], v[208:211], v[66:69]
	s_setprio 0
	s_barrier
	s_add_i32 s70, s70, s63
	v_lshl_add_u64 v[212:213], s[68:69], 0, v[186:187]
	s_mov_b32 m0, s70
	ds_read_b128 v[162:165], v226 offset:16384
	ds_read_b128 v[166:169], v226 offset:17408
	ds_read_b128 v[170:173], v226 offset:18432
	ds_read_b128 v[174:177], v226 offset:19456
	ds_read_b128 v[196:199], v226 offset:20480
	ds_read_b128 v[200:203], v226 offset:21504
	ds_read_b128 v[204:207], v226 offset:22528
	ds_read_b128 v[208:211], v226 offset:23552
	global_load_lds_dwordx4 v[212:213], off
	s_add_i32 m0, s70, 0x2000
	v_lshl_add_u64 v[214:215], s[68:69], 0, v[182:183]
	s_add_u32 s68, s68, s90
	s_addc_u32 s69, s69, 0
	s_add_i32 s70, s71, s63
	global_load_lds_dwordx4 v[214:215], off
	v_lshl_add_u64 v[216:217], s[68:69], 0, v[186:187]
	s_mov_b32 m0, s70
	v_lshl_add_u64 v[218:219], s[68:69], 0, v[182:183]
	global_load_lds_dwordx4 v[216:217], off
	s_add_i32 m0, s70, 0x2000
	v_lshl_add_u64 v[232:233], s[50:51], 0, v[184:185]
	global_load_lds_dwordx4 v[218:219], off
	s_mov_b32 m0, s67
	v_lshl_add_u64 v[234:235], s[50:51], 0, v[180:181]
	global_load_lds_dwordx4 v[232:233], off
	s_mov_b32 m0, s33
	s_nop 0
	global_load_lds_dwordx4 v[234:235], off
	s_waitcnt vmcnt(8)
	s_add_i32 s98, vcc_lo, -2
	s_cmp_lt_u32 s98, 16
	s_cbranch_scc0 .Lrk_dU_8_16
	s_cmp_lt_u32 s98, 8
	s_cbranch_scc0 .Lrk_dU_4_8
	s_cmp_lt_u32 s98, 4
	s_cbranch_scc0 .Lrk_dU_2_4
	s_cmp_lt_u32 s98, 2
	s_cbranch_scc0 .Lrk_dU_1_2
	v_add_f32_dpp v126, v240, v126 quad_perm:[0,1,2,3] row_mask:0xf bank_mask:0x3
	v_add_f32_dpp v127, v241, v127 quad_perm:[0,1,2,3] row_mask:0xf bank_mask:0x3
	v_add_f32_dpp v128, v242, v128 quad_perm:[0,1,2,3] row_mask:0xf bank_mask:0x3
	v_add_f32_dpp v129, v243, v129 quad_perm:[0,1,2,3] row_mask:0xf bank_mask:0x3
	v_add_f32_dpp v122, v240, v122 row_ror:8 row_mask:0xf bank_mask:0x3
	v_add_f32_dpp v123, v241, v123 row_ror:8 row_mask:0xf bank_mask:0x3
	v_add_f32_dpp v124, v242, v124 row_ror:8 row_mask:0xf bank_mask:0x3
	v_add_f32_dpp v125, v243, v125 row_ror:8 row_mask:0xf bank_mask:0x3
	s_branch .Lrk_joinU
.Lrk_dU_1_2:
	v_add_f32_dpp v110, v240, v110 quad_perm:[0,1,2,3] row_mask:0xf bank_mask:0x3
	v_add_f32_dpp v111, v241, v111 quad_perm:[0,1,2,3] row_mask:0xf bank_mask:0x3
	v_add_f32_dpp v112, v242, v112 quad_perm:[0,1,2,3] row_mask:0xf bank_mask:0x3
	v_add_f32_dpp v113, v243, v113 quad_perm:[0,1,2,3] row_mask:0xf bank_mask:0x3
	v_add_f32_dpp v106, v240, v106 row_ror:8 row_mask:0xf bank_mask:0x3
	v_add_f32_dpp v107, v241, v107 row_ror:8 row_mask:0xf bank_mask:0x3
	v_add_f32_dpp v108, v242, v108 row_ror:8 row_mask:0xf bank_mask:0x3
	v_add_f32_dpp v109, v243, v109 row_ror:8 row_mask:0xf bank_mask:0x3
	s_branch .Lrk_joinU
.Lrk_dU_2_4:
	s_cmp_lt_u32 s98, 6
	s_cbranch_scc0 .Lrk_dU_3_4
	v_add_f32_dpp v118, v240, v118 quad_perm:[0,1,2,3] row_mask:0xf bank_mask:0x3
	v_add_f32_dpp v119, v241, v119 quad_perm:[0,1,2,3] row_mask:0xf bank_mask:0x3
	v_add_f32_dpp v120, v242, v120 quad_perm:[0,1,2,3] row_mask:0xf bank_mask:0x3
	v_add_f32_dpp v121, v243, v121 quad_perm:[0,1,2,3] row_mask:0xf bank_mask:0x3
	v_add_f32_dpp v114, v240, v114 row_ror:8 row_mask:0xf bank_mask:0x3
	v_add_f32_dpp v115, v241, v115 row_ror:8 row_mask:0xf bank_mask:0x3
	v_add_f32_dpp v116, v242, v116 row_ror:8 row_mask:0xf bank_mask:0x3
	v_add_f32_dpp v117, v243, v117 row_ror:8 row_mask:0xf bank_mask:0x3
	s_branch .Lrk_joinU
.Lrk_dU_3_4:
	v_add_f32_dpp v94, v240, v94 quad_perm:[0,1,2,3] row_mask:0xf bank_mask:0x3
	v_add_f32_dpp v95, v241, v95 quad_perm:[0,1,2,3] row_mask:0xf bank_mask:0x3
	v_add_f32_dpp v96, v242, v96 quad_perm:[0,1,2,3] row_mask:0xf bank_mask:0x3
	v_add_f32_dpp v97, v243, v97 quad_perm:[0,1,2,3] row_mask:0xf bank_mask:0x3
	v_add_f32_dpp v90, v240, v90 row_ror:8 row_mask:0xf bank_mask:0x3
	v_add_f32_dpp v91, v241, v91 row_ror:8 row_mask:0xf bank_mask:0x3
	v_add_f32_dpp v92, v242, v92 row_ror:8 row_mask:0xf bank_mask:0x3
	v_add_f32_dpp v93, v243, v93 row_ror:8 row_mask:0xf bank_mask:0x3
	s_branch .Lrk_joinU
.Lrk_dU_4_8:
	s_cmp_lt_u32 s98, 12
	s_cbranch_scc0 .Lrk_dU_6_8
	s_cmp_lt_u32 s98, 10
	s_cbranch_scc0 .Lrk_dU_5_6
	v_add_f32_dpp v102, v240, v102 quad_perm:[0,1,2,3] row_mask:0xf bank_mask:0x3
	v_add_f32_dpp v103, v241, v103 quad_perm:[0,1,2,3] row_mask:0xf bank_mask:0x3
	v_add_f32_dpp v104, v242, v104 quad_perm:[0,1,2,3] row_mask:0xf bank_mask:0x3
	v_add_f32_dpp v105, v243, v105 quad_perm:[0,1,2,3] row_mask:0xf bank_mask:0x3
	v_add_f32_dpp v98, v240, v98 row_ror:8 row_mask:0xf bank_mask:0x3
	v_add_f32_dpp v99, v241, v99 row_ror:8 row_mask:0xf bank_mask:0x3
	v_add_f32_dpp v100, v242, v100 row_ror:8 row_mask:0xf bank_mask:0x3
	v_add_f32_dpp v101, v243, v101 row_ror:8 row_mask:0xf bank_mask:0x3
	s_branch .Lrk_joinU
.Lrk_dU_5_6:
	v_add_f32_dpp v78, v240, v78 quad_perm:[0,1,2,3] row_mask:0xf bank_mask:0x3
	v_add_f32_dpp v79, v241, v79 quad_perm:[0,1,2,3] row_mask:0xf bank_mask:0x3
	v_add_f32_dpp v80, v242, v80 quad_perm:[0,1,2,3] row_mask:0xf bank_mask:0x3
	v_add_f32_dpp v81, v243, v81 quad_perm:[0,1,2,3] row_mask:0xf bank_mask:0x3
	v_add_f32_dpp v74, v240, v74 row_ror:8 row_mask:0xf bank_mask:0x3
	v_add_f32_dpp v75, v241, v75 row_ror:8 row_mask:0xf bank_mask:0x3
	v_add_f32_dpp v76, v242, v76 row_ror:8 row_mask:0xf bank_mask:0x3
	v_add_f32_dpp v77, v243, v77 row_ror:8 row_mask:0xf bank_mask:0x3
	s_branch .Lrk_joinU
.Lrk_dU_6_8:
	s_cmp_lt_u32 s98, 14
	s_cbranch_scc0 .Lrk_dU_7_8
	v_add_f32_dpp v86, v240, v86 quad_perm:[0,1,2,3] row_mask:0xf bank_mask:0x3
	v_add_f32_dpp v87, v241, v87 quad_perm:[0,1,2,3] row_mask:0xf bank_mask:0x3
	v_add_f32_dpp v88, v242, v88 quad_perm:[0,1,2,3] row_mask:0xf bank_mask:0x3
	v_add_f32_dpp v89, v243, v89 quad_perm:[0,1,2,3] row_mask:0xf bank_mask:0x3
	v_add_f32_dpp v82, v240, v82 row_ror:8 row_mask:0xf bank_mask:0x3
	v_add_f32_dpp v83, v241, v83 row_ror:8 row_mask:0xf bank_mask:0x3
	v_add_f32_dpp v84, v242, v84 row_ror:8 row_mask:0xf bank_mask:0x3
	v_add_f32_dpp v85, v243, v85 row_ror:8 row_mask:0xf bank_mask:0x3
	s_branch .Lrk_joinU
.Lrk_dU_7_8:
	v_add_f32_dpp v70, v240, v70 quad_perm:[0,1,2,3] row_mask:0xf bank_mask:0x3
	v_add_f32_dpp v71, v241, v71 quad_perm:[0,1,2,3] row_mask:0xf bank_mask:0x3
	v_add_f32_dpp v72, v242, v72 quad_perm:[0,1,2,3] row_mask:0xf bank_mask:0x3
	v_add_f32_dpp v73, v243, v73 quad_perm:[0,1,2,3] row_mask:0xf bank_mask:0x3
	v_add_f32_dpp v66, v240, v66 row_ror:8 row_mask:0xf bank_mask:0x3
	v_add_f32_dpp v67, v241, v67 row_ror:8 row_mask:0xf bank_mask:0x3
	v_add_f32_dpp v68, v242, v68 row_ror:8 row_mask:0xf bank_mask:0x3
	v_add_f32_dpp v69, v243, v69 row_ror:8 row_mask:0xf bank_mask:0x3
	s_branch .Lrk_joinU
.Lrk_dU_8_16:
	s_cmp_lt_u32 s98, 24
	s_cbranch_scc0 .Lrk_dU_12_16
	s_cmp_lt_u32 s98, 20
	s_cbranch_scc0 .Lrk_dU_10_12
	s_cmp_lt_u32 s98, 18
	s_cbranch_scc0 .Lrk_dU_9_10
	v_add_f32_dpp v62, v240, v62 quad_perm:[0,1,2,3] row_mask:0xf bank_mask:0x3
	v_add_f32_dpp v63, v241, v63 quad_perm:[0,1,2,3] row_mask:0xf bank_mask:0x3
	v_add_f32_dpp v64, v242, v64 quad_perm:[0,1,2,3] row_mask:0xf bank_mask:0x3
	v_add_f32_dpp v65, v243, v65 quad_perm:[0,1,2,3] row_mask:0xf bank_mask:0x3
	v_add_f32_dpp v58, v240, v58 row_ror:8 row_mask:0xf bank_mask:0x3
	v_add_f32_dpp v59, v241, v59 row_ror:8 row_mask:0xf bank_mask:0x3
	v_add_f32_dpp v60, v242, v60 row_ror:8 row_mask:0xf bank_mask:0x3
	v_add_f32_dpp v61, v243, v61 row_ror:8 row_mask:0xf bank_mask:0x3
	s_branch .Lrk_joinU
.Lrk_dU_9_10:
	v_add_f32_dpp v46, v240, v46 quad_perm:[0,1,2,3] row_mask:0xf bank_mask:0x3
	v_add_f32_dpp v47, v241, v47 quad_perm:[0,1,2,3] row_mask:0xf bank_mask:0x3
	v_add_f32_dpp v48, v242, v48 quad_perm:[0,1,2,3] row_mask:0xf bank_mask:0x3
	v_add_f32_dpp v49, v243, v49 quad_perm:[0,1,2,3] row_mask:0xf bank_mask:0x3
	v_add_f32_dpp v42, v240, v42 row_ror:8 row_mask:0xf bank_mask:0x3
	v_add_f32_dpp v43, v241, v43 row_ror:8 row_mask:0xf bank_mask:0x3
	v_add_f32_dpp v44, v242, v44 row_ror:8 row_mask:0xf bank_mask:0x3
	v_add_f32_dpp v45, v243, v45 row_ror:8 row_mask:0xf bank_mask:0x3
	s_branch .Lrk_joinU
.Lrk_dU_10_12:
	s_cmp_lt_u32 s98, 22
	s_cbranch_scc0 .Lrk_dU_11_12
	v_add_f32_dpp v54, v240, v54 quad_perm:[0,1,2,3] row_mask:0xf bank_mask:0x3
	v_add_f32_dpp v55, v241, v55 quad_perm:[0,1,2,3] row_mask:0xf bank_mask:0x3
	v_add_f32_dpp v56, v242, v56 quad_perm:[0,1,2,3] row_mask:0xf bank_mask:0x3
	v_add_f32_dpp v57, v243, v57 quad_perm:[0,1,2,3] row_mask:0xf bank_mask:0x3
	v_add_f32_dpp v50, v240, v50 row_ror:8 row_mask:0xf bank_mask:0x3
	v_add_f32_dpp v51, v241, v51 row_ror:8 row_mask:0xf bank_mask:0x3
	v_add_f32_dpp v52, v242, v52 row_ror:8 row_mask:0xf bank_mask:0x3
	v_add_f32_dpp v53, v243, v53 row_ror:8 row_mask:0xf bank_mask:0x3
	s_branch .Lrk_joinU
.Lrk_dU_11_12:
	v_add_f32_dpp v30, v240, v30 quad_perm:[0,1,2,3] row_mask:0xf bank_mask:0x3
	v_add_f32_dpp v31, v241, v31 quad_perm:[0,1,2,3] row_mask:0xf bank_mask:0x3
	v_add_f32_dpp v32, v242, v32 quad_perm:[0,1,2,3] row_mask:0xf bank_mask:0x3
	v_add_f32_dpp v33, v243, v33 quad_perm:[0,1,2,3] row_mask:0xf bank_mask:0x3
	v_add_f32_dpp v26, v240, v26 row_ror:8 row_mask:0xf bank_mask:0x3
	v_add_f32_dpp v27, v241, v27 row_ror:8 row_mask:0xf bank_mask:0x3
	v_add_f32_dpp v28, v242, v28 row_ror:8 row_mask:0xf bank_mask:0x3
	v_add_f32_dpp v29, v243, v29 row_ror:8 row_mask:0xf bank_mask:0x3
	s_branch .Lrk_joinU
.Lrk_dU_12_16:
	s_cmp_lt_u32 s98, 28
	s_cbranch_scc0 .Lrk_dU_14_16
	s_cmp_lt_u32 s98, 26
	s_cbranch_scc0 .Lrk_dU_13_14
	v_add_f32_dpp v38, v240, v38 quad_perm:[0,1,2,3] row_mask:0xf bank_mask:0x3
	v_add_f32_dpp v39, v241, v39 quad_perm:[0,1,2,3] row_mask:0xf bank_mask:0x3
	v_add_f32_dpp v40, v242, v40 quad_perm:[0,1,2,3] row_mask:0xf bank_mask:0x3
	v_add_f32_dpp v41, v243, v41 quad_perm:[0,1,2,3] row_mask:0xf bank_mask:0x3
	v_add_f32_dpp v34, v240, v34 row_ror:8 row_mask:0xf bank_mask:0x3
	v_add_f32_dpp v35, v241, v35 row_ror:8 row_mask:0xf bank_mask:0x3
	v_add_f32_dpp v36, v242, v36 row_ror:8 row_mask:0xf bank_mask:0x3
	v_add_f32_dpp v37, v243, v37 row_ror:8 row_mask:0xf bank_mask:0x3
	s_branch .Lrk_joinU
.Lrk_dU_13_14:
	v_add_f32_dpp v14, v240, v14 quad_perm:[0,1,2,3] row_mask:0xf bank_mask:0x3
	v_add_f32_dpp v15, v241, v15 quad_perm:[0,1,2,3] row_mask:0xf bank_mask:0x3
	v_add_f32_dpp v16, v242, v16 quad_perm:[0,1,2,3] row_mask:0xf bank_mask:0x3
	v_add_f32_dpp v17, v243, v17 quad_perm:[0,1,2,3] row_mask:0xf bank_mask:0x3
	v_add_f32_dpp v10, v240, v10 row_ror:8 row_mask:0xf bank_mask:0x3
	v_add_f32_dpp v11, v241, v11 row_ror:8 row_mask:0xf bank_mask:0x3
	v_add_f32_dpp v12, v242, v12 row_ror:8 row_mask:0xf bank_mask:0x3
	v_add_f32_dpp v13, v243, v13 row_ror:8 row_mask:0xf bank_mask:0x3
	s_branch .Lrk_joinU
.Lrk_dU_14_16:
	s_cmp_lt_u32 s98, 30
	s_cbranch_scc0 .Lrk_dU_15_16
	v_add_f32_dpp v22, v240, v22 quad_perm:[0,1,2,3] row_mask:0xf bank_mask:0x3
	v_add_f32_dpp v23, v241, v23 quad_perm:[0,1,2,3] row_mask:0xf bank_mask:0x3
	v_add_f32_dpp v24, v242, v24 quad_perm:[0,1,2,3] row_mask:0xf bank_mask:0x3
	v_add_f32_dpp v25, v243, v25 quad_perm:[0,1,2,3] row_mask:0xf bank_mask:0x3
	v_add_f32_dpp v18, v240, v18 row_ror:8 row_mask:0xf bank_mask:0x3
	v_add_f32_dpp v19, v241, v19 row_ror:8 row_mask:0xf bank_mask:0x3
	v_add_f32_dpp v20, v242, v20 row_ror:8 row_mask:0xf bank_mask:0x3
	v_add_f32_dpp v21, v243, v21 row_ror:8 row_mask:0xf bank_mask:0x3
	s_branch .Lrk_joinU
.Lrk_dU_15_16:
	v_add_f32_dpp v6, v240, v6 quad_perm:[0,1,2,3] row_mask:0xf bank_mask:0x3
	v_add_f32_dpp v7, v241, v7 quad_perm:[0,1,2,3] row_mask:0xf bank_mask:0x3
	v_add_f32_dpp v8, v242, v8 quad_perm:[0,1,2,3] row_mask:0xf bank_mask:0x3
	v_add_f32_dpp v9, v243, v9 quad_perm:[0,1,2,3] row_mask:0xf bank_mask:0x3
	v_add_f32_dpp v2, v240, v2 row_ror:8 row_mask:0xf bank_mask:0x3
	v_add_f32_dpp v3, v241, v3 row_ror:8 row_mask:0xf bank_mask:0x3
	v_add_f32_dpp v4, v242, v4 row_ror:8 row_mask:0xf bank_mask:0x3
	v_add_f32_dpp v5, v243, v5 row_ror:8 row_mask:0xf bank_mask:0x3
	s_branch .Lrk_joinU
.Lrk_joinU:
	s_waitcnt lgkmcnt(0)
	s_barrier
	s_setprio 1
	s_waitcnt lgkmcnt(0)
	v_mfma_f32_16x16x32_bf16 v[62:65], v[130:133], v[162:165], v[62:65]
	v_mfma_f32_16x16x32_bf16 v[58:61], v[138:141], v[162:165], v[58:61]
	v_mfma_f32_16x16x32_bf16 v[54:57], v[130:133], v[170:173], v[54:57]
	v_mfma_f32_16x16x32_bf16 v[50:53], v[138:141], v[170:173], v[50:53]
	v_mfma_f32_16x16x32_bf16 v[38:41], v[130:133], v[196:199], v[38:41]
	v_mfma_f32_16x16x32_bf16 v[34:37], v[138:141], v[196:199], v[34:37]
	v_mfma_f32_16x16x32_bf16 v[22:25], v[130:133], v[204:207], v[22:25]
	v_mfma_f32_16x16x32_bf16 v[18:21], v[138:141], v[204:207], v[18:21]
	v_mfma_f32_16x16x32_bf16 v[62:65], v[134:137], v[166:169], v[62:65]
	v_mfma_f32_16x16x32_bf16 v[58:61], v[142:145], v[166:169], v[58:61]
	v_mfma_f32_16x16x32_bf16 v[54:57], v[134:137], v[174:177], v[54:57]
	v_mfma_f32_16x16x32_bf16 v[50:53], v[142:145], v[174:177], v[50:53]
	v_mfma_f32_16x16x32_bf16 v[38:41], v[134:137], v[200:203], v[38:41]
	v_mfma_f32_16x16x32_bf16 v[34:37], v[142:145], v[200:203], v[34:37]
	v_mfma_f32_16x16x32_bf16 v[22:25], v[134:137], v[208:211], v[22:25]
	v_mfma_f32_16x16x32_bf16 v[18:21], v[142:145], v[208:211], v[18:21]
	s_setprio 0
	s_setprio 1
	v_mfma_f32_16x16x32_bf16 v[46:49], v[146:149], v[162:165], v[46:49]
	v_mfma_f32_16x16x32_bf16 v[42:45], v[154:157], v[162:165], v[42:45]
	v_mfma_f32_16x16x32_bf16 v[30:33], v[146:149], v[170:173], v[30:33]
	v_mfma_f32_16x16x32_bf16 v[26:29], v[154:157], v[170:173], v[26:29]
	v_mfma_f32_16x16x32_bf16 v[14:17], v[146:149], v[196:199], v[14:17]
	v_mfma_f32_16x16x32_bf16 v[10:13], v[154:157], v[196:199], v[10:13]
	v_mfma_f32_16x16x32_bf16 v[6:9], v[146:149], v[204:207], v[6:9]
	v_mfma_f32_16x16x32_bf16 v[2:5], v[154:157], v[204:207], v[2:5]
	v_mfma_f32_16x16x32_bf16 v[46:49], v[150:153], v[166:169], v[46:49]
	v_mfma_f32_16x16x32_bf16 v[42:45], v[158:161], v[166:169], v[42:45]
	v_mfma_f32_16x16x32_bf16 v[30:33], v[150:153], v[174:177], v[30:33]
	v_mfma_f32_16x16x32_bf16 v[26:29], v[158:161], v[174:177], v[26:29]
	v_mfma_f32_16x16x32_bf16 v[14:17], v[150:153], v[200:203], v[14:17]
	v_mfma_f32_16x16x32_bf16 v[10:13], v[158:161], v[200:203], v[10:13]
	v_mfma_f32_16x16x32_bf16 v[6:9], v[150:153], v[208:211], v[6:9]
	v_mfma_f32_16x16x32_bf16 v[2:5], v[158:161], v[208:211], v[2:5]
	s_setprio 0
	s_barrier
	s_add_i32 s68, 0, 0x18000
	v_add_u32_e32 v0, s68, v223
	s_add_i32 s69, 0, 0x1c000
	ds_read_b128 v[130:133], v0
	ds_read_b128 v[134:137], v0 offset:1024
	ds_read_b128 v[138:141], v0 offset:2048
	ds_read_b128 v[142:145], v0 offset:3072
	v_add_u32_e32 v0, s69, v223
	ds_read_b128 v[146:149], v0
	ds_read_b128 v[150:153], v0 offset:1024
	ds_read_b128 v[154:157], v0 offset:2048
	ds_read_b128 v[158:161], v0 offset:3072
	s_add_u32 s50, s50, s90
	s_addc_u32 s51, s51, 0
	s_mov_b32 m0, s65
	s_add_i32 s98, vcc_lo, -2
	s_and_b32 s99, s98, 2
	s_lshl_b32 s99, s99, 8
	s_lshr_b32 vcc_hi, s98, 2
	s_and_b32 vcc_hi, vcc_hi, 3
	s_lshl_b32 vcc_hi, vcc_hi, 17
	s_or_b32 s99, s99, vcc_hi
	s_lshr_b32 vcc_hi, s98, 4
	s_lshl_b32 vcc_hi, vcc_hi, 20
	s_or_b32 s98, s99, vcc_hi
	s_add_u32 s98, s100, s98
	s_addc_u32 s99, s101, 0
	s_nop 0
	global_load_dwordx4 v[240:243], v239, s[98:99]
	v_lshl_add_u64 v[236:237], s[50:51], 0, v[184:185]
	ds_read_b128 v[162:165], v226 offset:32768
	ds_read_b128 v[166:169], v226 offset:33792
	ds_read_b128 v[170:173], v226 offset:34816
	ds_read_b128 v[174:177], v226 offset:35840
	ds_read_b128 v[196:199], v226 offset:36864
	ds_read_b128 v[200:203], v226 offset:37888
	ds_read_b128 v[204:207], v226 offset:38912
	ds_read_b128 v[208:211], v226 offset:39936
	global_load_lds_dwordx4 v[236:237], off
	v_lshl_add_u64 v[236:237], s[50:51], 0, v[180:181]
	s_mov_b32 m0, s22
	s_nop 0
	global_load_lds_dwordx4 v[236:237], off
	s_waitcnt vmcnt(9)
	s_waitcnt lgkmcnt(0)
	s_barrier
	s_setprio 1
	s_waitcnt lgkmcnt(0)
	v_mfma_f32_16x16x32_bf16 v[126:129], v[130:133], v[162:165], v[126:129]
	v_mfma_f32_16x16x32_bf16 v[122:125], v[138:141], v[162:165], v[122:125]
	v_mfma_f32_16x16x32_bf16 v[118:121], v[130:133], v[170:173], v[118:121]
	v_mfma_f32_16x16x32_bf16 v[114:117], v[138:141], v[170:173], v[114:117]
	v_mfma_f32_16x16x32_bf16 v[102:105], v[130:133], v[196:199], v[102:105]
	v_mfma_f32_16x16x32_bf16 v[98:101], v[138:141], v[196:199], v[98:101]
	v_mfma_f32_16x16x32_bf16 v[86:89], v[130:133], v[204:207], v[86:89]
	v_mfma_f32_16x16x32_bf16 v[82:85], v[138:141], v[204:207], v[82:85]
	v_mfma_f32_16x16x32_bf16 v[126:129], v[134:137], v[166:169], v[126:129]
	v_mfma_f32_16x16x32_bf16 v[122:125], v[142:145], v[166:169], v[122:125]
	v_mfma_f32_16x16x32_bf16 v[118:121], v[134:137], v[174:177], v[118:121]
	v_mfma_f32_16x16x32_bf16 v[114:117], v[142:145], v[174:177], v[114:117]
	v_mfma_f32_16x16x32_bf16 v[102:105], v[134:137], v[200:203], v[102:105]
	v_mfma_f32_16x16x32_bf16 v[98:101], v[142:145], v[200:203], v[98:101]
	v_mfma_f32_16x16x32_bf16 v[86:89], v[134:137], v[208:211], v[86:89]
	v_mfma_f32_16x16x32_bf16 v[82:85], v[142:145], v[208:211], v[82:85]
	s_setprio 0
	s_setprio 1
	v_mfma_f32_16x16x32_bf16 v[110:113], v[146:149], v[162:165], v[110:113]
	v_mfma_f32_16x16x32_bf16 v[106:109], v[154:157], v[162:165], v[106:109]
	v_mfma_f32_16x16x32_bf16 v[94:97], v[146:149], v[170:173], v[94:97]
	v_mfma_f32_16x16x32_bf16 v[90:93], v[154:157], v[170:173], v[90:93]
	v_mfma_f32_16x16x32_bf16 v[78:81], v[146:149], v[196:199], v[78:81]
	v_mfma_f32_16x16x32_bf16 v[74:77], v[154:157], v[196:199], v[74:77]
	v_mfma_f32_16x16x32_bf16 v[70:73], v[146:149], v[204:207], v[70:73]
	v_mfma_f32_16x16x32_bf16 v[66:69], v[154:157], v[204:207], v[66:69]
	v_mfma_f32_16x16x32_bf16 v[110:113], v[150:153], v[166:169], v[110:113]
	v_mfma_f32_16x16x32_bf16 v[106:109], v[158:161], v[166:169], v[106:109]
	v_mfma_f32_16x16x32_bf16 v[94:97], v[150:153], v[174:177], v[94:97]
	v_mfma_f32_16x16x32_bf16 v[90:93], v[158:161], v[174:177], v[90:93]
	v_mfma_f32_16x16x32_bf16 v[78:81], v[150:153], v[200:203], v[78:81]
	v_mfma_f32_16x16x32_bf16 v[74:77], v[158:161], v[200:203], v[74:77]
	v_mfma_f32_16x16x32_bf16 v[70:73], v[150:153], v[208:211], v[70:73]
	v_mfma_f32_16x16x32_bf16 v[66:69], v[158:161], v[208:211], v[66:69]
	s_setprio 0
	s_barrier
	s_add_i32 s50, s68, s63
	v_lshl_add_u64 v[212:213], v[212:213], 0, s[94:95]
	s_mov_b32 m0, s50
	ds_read_b128 v[162:165], v226 offset:49152
	ds_read_b128 v[166:169], v226 offset:50176
	ds_read_b128 v[170:173], v226 offset:51200
	ds_read_b128 v[174:177], v226 offset:52224
	ds_read_b128 v[196:199], v226 offset:53248
	ds_read_b128 v[200:203], v226 offset:54272
	ds_read_b128 v[204:207], v226 offset:55296
	ds_read_b128 v[208:211], v226 offset:56320
	global_load_lds_dwordx4 v[212:213], off
	v_lshl_add_u64 v[212:213], v[214:215], 0, s[94:95]
	s_add_i32 m0, s50, 0x2000
	s_add_i32 s50, s69, s63
	global_load_lds_dwordx4 v[212:213], off
	v_lshl_add_u64 v[212:213], v[216:217], 0, s[94:95]
	s_mov_b32 m0, s50
	s_nop 0
	global_load_lds_dwordx4 v[212:213], off
	v_lshl_add_u64 v[212:213], v[218:219], 0, s[94:95]
	s_add_i32 m0, s50, 0x2000
	s_nop 0
	global_load_lds_dwordx4 v[212:213], off
	v_lshl_add_u64 v[212:213], v[232:233], 0, s[94:95]
	s_mov_b32 m0, s87
	s_nop 0
	global_load_lds_dwordx4 v[212:213], off
	v_lshl_add_u64 v[212:213], v[234:235], 0, s[94:95]
	s_mov_b32 m0, s2
	s_nop 0
	global_load_lds_dwordx4 v[212:213], off
	s_waitcnt vmcnt(8)
	s_add_i32 s98, vcc_lo, -2
	s_cmp_lt_u32 s98, 16
	s_cbranch_scc0 .Lrk_dL_8_16
	s_cmp_lt_u32 s98, 8
	s_cbranch_scc0 .Lrk_dL_4_8
	s_cmp_lt_u32 s98, 4
	s_cbranch_scc0 .Lrk_dL_2_4
	s_cmp_lt_u32 s98, 2
	s_cbranch_scc0 .Lrk_dL_1_2
	v_add_f32_dpp v126, v240, v126 row_ror:8 row_mask:0xf bank_mask:0xc
	v_add_f32_dpp v127, v241, v127 row_ror:8 row_mask:0xf bank_mask:0xc
	v_add_f32_dpp v128, v242, v128 row_ror:8 row_mask:0xf bank_mask:0xc
	v_add_f32_dpp v129, v243, v129 row_ror:8 row_mask:0xf bank_mask:0xc
	v_add_f32_dpp v122, v240, v122 quad_perm:[0,1,2,3] row_mask:0xf bank_mask:0xc
	v_add_f32_dpp v123, v241, v123 quad_perm:[0,1,2,3] row_mask:0xf bank_mask:0xc
	v_add_f32_dpp v124, v242, v124 quad_perm:[0,1,2,3] row_mask:0xf bank_mask:0xc
	v_add_f32_dpp v125, v243, v125 quad_perm:[0,1,2,3] row_mask:0xf bank_mask:0xc
	s_branch .Lrk_joinL
.Lrk_dL_1_2:
	v_add_f32_dpp v110, v240, v110 row_ror:8 row_mask:0xf bank_mask:0xc
	v_add_f32_dpp v111, v241, v111 row_ror:8 row_mask:0xf bank_mask:0xc
	v_add_f32_dpp v112, v242, v112 row_ror:8 row_mask:0xf bank_mask:0xc
	v_add_f32_dpp v113, v243, v113 row_ror:8 row_mask:0xf bank_mask:0xc
	v_add_f32_dpp v106, v240, v106 quad_perm:[0,1,2,3] row_mask:0xf bank_mask:0xc
	v_add_f32_dpp v107, v241, v107 quad_perm:[0,1,2,3] row_mask:0xf bank_mask:0xc
	v_add_f32_dpp v108, v242, v108 quad_perm:[0,1,2,3] row_mask:0xf bank_mask:0xc
	v_add_f32_dpp v109, v243, v109 quad_perm:[0,1,2,3] row_mask:0xf bank_mask:0xc
	s_branch .Lrk_joinL
.Lrk_dL_2_4:
	s_cmp_lt_u32 s98, 6
	s_cbranch_scc0 .Lrk_dL_3_4
	v_add_f32_dpp v118, v240, v118 row_ror:8 row_mask:0xf bank_mask:0xc
	v_add_f32_dpp v119, v241, v119 row_ror:8 row_mask:0xf bank_mask:0xc
	v_add_f32_dpp v120, v242, v120 row_ror:8 row_mask:0xf bank_mask:0xc
	v_add_f32_dpp v121, v243, v121 row_ror:8 row_mask:0xf bank_mask:0xc
	v_add_f32_dpp v114, v240, v114 quad_perm:[0,1,2,3] row_mask:0xf bank_mask:0xc
	v_add_f32_dpp v115, v241, v115 quad_perm:[0,1,2,3] row_mask:0xf bank_mask:0xc
	v_add_f32_dpp v116, v242, v116 quad_perm:[0,1,2,3] row_mask:0xf bank_mask:0xc
	v_add_f32_dpp v117, v243, v117 quad_perm:[0,1,2,3] row_mask:0xf bank_mask:0xc
	s_branch .Lrk_joinL
.Lrk_dL_3_4:
	v_add_f32_dpp v94, v240, v94 row_ror:8 row_mask:0xf bank_mask:0xc
	v_add_f32_dpp v95, v241, v95 row_ror:8 row_mask:0xf bank_mask:0xc
	v_add_f32_dpp v96, v242, v96 row_ror:8 row_mask:0xf bank_mask:0xc
	v_add_f32_dpp v97, v243, v97 row_ror:8 row_mask:0xf bank_mask:0xc
	v_add_f32_dpp v90, v240, v90 quad_perm:[0,1,2,3] row_mask:0xf bank_mask:0xc
	v_add_f32_dpp v91, v241, v91 quad_perm:[0,1,2,3] row_mask:0xf bank_mask:0xc
	v_add_f32_dpp v92, v242, v92 quad_perm:[0,1,2,3] row_mask:0xf bank_mask:0xc
	v_add_f32_dpp v93, v243, v93 quad_perm:[0,1,2,3] row_mask:0xf bank_mask:0xc
	s_branch .Lrk_joinL
.Lrk_dL_4_8:
	s_cmp_lt_u32 s98, 12
	s_cbranch_scc0 .Lrk_dL_6_8
	s_cmp_lt_u32 s98, 10
	s_cbranch_scc0 .Lrk_dL_5_6
	v_add_f32_dpp v102, v240, v102 row_ror:8 row_mask:0xf bank_mask:0xc
	v_add_f32_dpp v103, v241, v103 row_ror:8 row_mask:0xf bank_mask:0xc
	v_add_f32_dpp v104, v242, v104 row_ror:8 row_mask:0xf bank_mask:0xc
	v_add_f32_dpp v105, v243, v105 row_ror:8 row_mask:0xf bank_mask:0xc
	v_add_f32_dpp v98, v240, v98 quad_perm:[0,1,2,3] row_mask:0xf bank_mask:0xc
	v_add_f32_dpp v99, v241, v99 quad_perm:[0,1,2,3] row_mask:0xf bank_mask:0xc
	v_add_f32_dpp v100, v242, v100 quad_perm:[0,1,2,3] row_mask:0xf bank_mask:0xc
	v_add_f32_dpp v101, v243, v101 quad_perm:[0,1,2,3] row_mask:0xf bank_mask:0xc
	s_branch .Lrk_joinL
.Lrk_dL_5_6:
	v_add_f32_dpp v78, v240, v78 row_ror:8 row_mask:0xf bank_mask:0xc
	v_add_f32_dpp v79, v241, v79 row_ror:8 row_mask:0xf bank_mask:0xc
	v_add_f32_dpp v80, v242, v80 row_ror:8 row_mask:0xf bank_mask:0xc
	v_add_f32_dpp v81, v243, v81 row_ror:8 row_mask:0xf bank_mask:0xc
	v_add_f32_dpp v74, v240, v74 quad_perm:[0,1,2,3] row_mask:0xf bank_mask:0xc
	v_add_f32_dpp v75, v241, v75 quad_perm:[0,1,2,3] row_mask:0xf bank_mask:0xc
	v_add_f32_dpp v76, v242, v76 quad_perm:[0,1,2,3] row_mask:0xf bank_mask:0xc
	v_add_f32_dpp v77, v243, v77 quad_perm:[0,1,2,3] row_mask:0xf bank_mask:0xc
	s_branch .Lrk_joinL
.Lrk_dL_6_8:
	s_cmp_lt_u32 s98, 14
	s_cbranch_scc0 .Lrk_dL_7_8
	v_add_f32_dpp v86, v240, v86 row_ror:8 row_mask:0xf bank_mask:0xc
	v_add_f32_dpp v87, v241, v87 row_ror:8 row_mask:0xf bank_mask:0xc
	v_add_f32_dpp v88, v242, v88 row_ror:8 row_mask:0xf bank_mask:0xc
	v_add_f32_dpp v89, v243, v89 row_ror:8 row_mask:0xf bank_mask:0xc
	v_add_f32_dpp v82, v240, v82 quad_perm:[0,1,2,3] row_mask:0xf bank_mask:0xc
	v_add_f32_dpp v83, v241, v83 quad_perm:[0,1,2,3] row_mask:0xf bank_mask:0xc
	v_add_f32_dpp v84, v242, v84 quad_perm:[0,1,2,3] row_mask:0xf bank_mask:0xc
	v_add_f32_dpp v85, v243, v85 quad_perm:[0,1,2,3] row_mask:0xf bank_mask:0xc
	s_branch .Lrk_joinL
.Lrk_dL_7_8:
	v_add_f32_dpp v70, v240, v70 row_ror:8 row_mask:0xf bank_mask:0xc
	v_add_f32_dpp v71, v241, v71 row_ror:8 row_mask:0xf bank_mask:0xc
	v_add_f32_dpp v72, v242, v72 row_ror:8 row_mask:0xf bank_mask:0xc
	v_add_f32_dpp v73, v243, v73 row_ror:8 row_mask:0xf bank_mask:0xc
	v_add_f32_dpp v66, v240, v66 quad_perm:[0,1,2,3] row_mask:0xf bank_mask:0xc
	v_add_f32_dpp v67, v241, v67 quad_perm:[0,1,2,3] row_mask:0xf bank_mask:0xc
	v_add_f32_dpp v68, v242, v68 quad_perm:[0,1,2,3] row_mask:0xf bank_mask:0xc
	v_add_f32_dpp v69, v243, v69 quad_perm:[0,1,2,3] row_mask:0xf bank_mask:0xc
	s_branch .Lrk_joinL
.Lrk_dL_8_16:
	s_cmp_lt_u32 s98, 24
	s_cbranch_scc0 .Lrk_dL_12_16
	s_cmp_lt_u32 s98, 20
	s_cbranch_scc0 .Lrk_dL_10_12
	s_cmp_lt_u32 s98, 18
	s_cbranch_scc0 .Lrk_dL_9_10
	v_add_f32_dpp v62, v240, v62 row_ror:8 row_mask:0xf bank_mask:0xc
	v_add_f32_dpp v63, v241, v63 row_ror:8 row_mask:0xf bank_mask:0xc
	v_add_f32_dpp v64, v242, v64 row_ror:8 row_mask:0xf bank_mask:0xc
	v_add_f32_dpp v65, v243, v65 row_ror:8 row_mask:0xf bank_mask:0xc
	v_add_f32_dpp v58, v240, v58 quad_perm:[0,1,2,3] row_mask:0xf bank_mask:0xc
	v_add_f32_dpp v59, v241, v59 quad_perm:[0,1,2,3] row_mask:0xf bank_mask:0xc
	v_add_f32_dpp v60, v242, v60 quad_perm:[0,1,2,3] row_mask:0xf bank_mask:0xc
	v_add_f32_dpp v61, v243, v61 quad_perm:[0,1,2,3] row_mask:0xf bank_mask:0xc
	s_branch .Lrk_joinL
.Lrk_dL_9_10:
	v_add_f32_dpp v46, v240, v46 row_ror:8 row_mask:0xf bank_mask:0xc
	v_add_f32_dpp v47, v241, v47 row_ror:8 row_mask:0xf bank_mask:0xc
	v_add_f32_dpp v48, v242, v48 row_ror:8 row_mask:0xf bank_mask:0xc
	v_add_f32_dpp v49, v243, v49 row_ror:8 row_mask:0xf bank_mask:0xc
	v_add_f32_dpp v42, v240, v42 quad_perm:[0,1,2,3] row_mask:0xf bank_mask:0xc
	v_add_f32_dpp v43, v241, v43 quad_perm:[0,1,2,3] row_mask:0xf bank_mask:0xc
	v_add_f32_dpp v44, v242, v44 quad_perm:[0,1,2,3] row_mask:0xf bank_mask:0xc
	v_add_f32_dpp v45, v243, v45 quad_perm:[0,1,2,3] row_mask:0xf bank_mask:0xc
	s_branch .Lrk_joinL
.Lrk_dL_10_12:
	s_cmp_lt_u32 s98, 22
	s_cbranch_scc0 .Lrk_dL_11_12
	v_add_f32_dpp v54, v240, v54 row_ror:8 row_mask:0xf bank_mask:0xc
	v_add_f32_dpp v55, v241, v55 row_ror:8 row_mask:0xf bank_mask:0xc
	v_add_f32_dpp v56, v242, v56 row_ror:8 row_mask:0xf bank_mask:0xc
	v_add_f32_dpp v57, v243, v57 row_ror:8 row_mask:0xf bank_mask:0xc
	v_add_f32_dpp v50, v240, v50 quad_perm:[0,1,2,3] row_mask:0xf bank_mask:0xc
	v_add_f32_dpp v51, v241, v51 quad_perm:[0,1,2,3] row_mask:0xf bank_mask:0xc
	v_add_f32_dpp v52, v242, v52 quad_perm:[0,1,2,3] row_mask:0xf bank_mask:0xc
	v_add_f32_dpp v53, v243, v53 quad_perm:[0,1,2,3] row_mask:0xf bank_mask:0xc
	s_branch .Lrk_joinL
.Lrk_dL_11_12:
	v_add_f32_dpp v30, v240, v30 row_ror:8 row_mask:0xf bank_mask:0xc
	v_add_f32_dpp v31, v241, v31 row_ror:8 row_mask:0xf bank_mask:0xc
	v_add_f32_dpp v32, v242, v32 row_ror:8 row_mask:0xf bank_mask:0xc
	v_add_f32_dpp v33, v243, v33 row_ror:8 row_mask:0xf bank_mask:0xc
	v_add_f32_dpp v26, v240, v26 quad_perm:[0,1,2,3] row_mask:0xf bank_mask:0xc
	v_add_f32_dpp v27, v241, v27 quad_perm:[0,1,2,3] row_mask:0xf bank_mask:0xc
	v_add_f32_dpp v28, v242, v28 quad_perm:[0,1,2,3] row_mask:0xf bank_mask:0xc
	v_add_f32_dpp v29, v243, v29 quad_perm:[0,1,2,3] row_mask:0xf bank_mask:0xc
	s_branch .Lrk_joinL
.Lrk_dL_12_16:
	s_cmp_lt_u32 s98, 28
	s_cbranch_scc0 .Lrk_dL_14_16
	s_cmp_lt_u32 s98, 26
	s_cbranch_scc0 .Lrk_dL_13_14
	v_add_f32_dpp v38, v240, v38 row_ror:8 row_mask:0xf bank_mask:0xc
	v_add_f32_dpp v39, v241, v39 row_ror:8 row_mask:0xf bank_mask:0xc
	v_add_f32_dpp v40, v242, v40 row_ror:8 row_mask:0xf bank_mask:0xc
	v_add_f32_dpp v41, v243, v41 row_ror:8 row_mask:0xf bank_mask:0xc
	v_add_f32_dpp v34, v240, v34 quad_perm:[0,1,2,3] row_mask:0xf bank_mask:0xc
	v_add_f32_dpp v35, v241, v35 quad_perm:[0,1,2,3] row_mask:0xf bank_mask:0xc
	v_add_f32_dpp v36, v242, v36 quad_perm:[0,1,2,3] row_mask:0xf bank_mask:0xc
	v_add_f32_dpp v37, v243, v37 quad_perm:[0,1,2,3] row_mask:0xf bank_mask:0xc
	s_branch .Lrk_joinL
.Lrk_dL_13_14:
	v_add_f32_dpp v14, v240, v14 row_ror:8 row_mask:0xf bank_mask:0xc
	v_add_f32_dpp v15, v241, v15 row_ror:8 row_mask:0xf bank_mask:0xc
	v_add_f32_dpp v16, v242, v16 row_ror:8 row_mask:0xf bank_mask:0xc
	v_add_f32_dpp v17, v243, v17 row_ror:8 row_mask:0xf bank_mask:0xc
	v_add_f32_dpp v10, v240, v10 quad_perm:[0,1,2,3] row_mask:0xf bank_mask:0xc
	v_add_f32_dpp v11, v241, v11 quad_perm:[0,1,2,3] row_mask:0xf bank_mask:0xc
	v_add_f32_dpp v12, v242, v12 quad_perm:[0,1,2,3] row_mask:0xf bank_mask:0xc
	v_add_f32_dpp v13, v243, v13 quad_perm:[0,1,2,3] row_mask:0xf bank_mask:0xc
	s_branch .Lrk_joinL
.Lrk_dL_14_16:
	s_cmp_lt_u32 s98, 30
	s_cbranch_scc0 .Lrk_dL_15_16
	v_add_f32_dpp v22, v240, v22 row_ror:8 row_mask:0xf bank_mask:0xc
	v_add_f32_dpp v23, v241, v23 row_ror:8 row_mask:0xf bank_mask:0xc
	v_add_f32_dpp v24, v242, v24 row_ror:8 row_mask:0xf bank_mask:0xc
	v_add_f32_dpp v25, v243, v25 row_ror:8 row_mask:0xf bank_mask:0xc
	v_add_f32_dpp v18, v240, v18 quad_perm:[0,1,2,3] row_mask:0xf bank_mask:0xc
	v_add_f32_dpp v19, v241, v19 quad_perm:[0,1,2,3] row_mask:0xf bank_mask:0xc
	v_add_f32_dpp v20, v242, v20 quad_perm:[0,1,2,3] row_mask:0xf bank_mask:0xc
	v_add_f32_dpp v21, v243, v21 quad_perm:[0,1,2,3] row_mask:0xf bank_mask:0xc
	s_branch .Lrk_joinL
.Lrk_dL_15_16:
	v_add_f32_dpp v6, v240, v6 row_ror:8 row_mask:0xf bank_mask:0xc
	v_add_f32_dpp v7, v241, v7 row_ror:8 row_mask:0xf bank_mask:0xc
	v_add_f32_dpp v8, v242, v8 row_ror:8 row_mask:0xf bank_mask:0xc
	v_add_f32_dpp v9, v243, v9 row_ror:8 row_mask:0xf bank_mask:0xc
	v_add_f32_dpp v2, v240, v2 quad_perm:[0,1,2,3] row_mask:0xf bank_mask:0xc
	v_add_f32_dpp v3, v241, v3 quad_perm:[0,1,2,3] row_mask:0xf bank_mask:0xc
	v_add_f32_dpp v4, v242, v4 quad_perm:[0,1,2,3] row_mask:0xf bank_mask:0xc
	v_add_f32_dpp v5, v243, v5 quad_perm:[0,1,2,3] row_mask:0xf bank_mask:0xc
	s_branch .Lrk_joinL

.LBB0_343:
	s_add_i32 s15, s55, -2
	s_add_u32 s48, s48, 0x80
	s_addc_u32 s49, s49, 0
	s_add_u32 s56, s50, 0x100
	v_mov_b32_e32 v2, 0
	s_addc_u32 s57, s51, 0
	s_mov_b32 s50, 0
	v_mov_b32_e32 v3, v2
	v_mov_b32_e32 v4, v2
	v_mov_b32_e32 v5, v2
	v_mov_b32_e32 v6, v2
	v_mov_b32_e32 v7, v2
	v_mov_b32_e32 v8, v2
	v_mov_b32_e32 v9, v2
	v_mov_b32_e32 v10, v2
	v_mov_b32_e32 v11, v2
	v_mov_b32_e32 v12, v2
	v_mov_b32_e32 v13, v2
	v_mov_b32_e32 v14, v2
	v_mov_b32_e32 v15, v2
	v_mov_b32_e32 v16, v2
	v_mov_b32_e32 v17, v2
	v_mov_b32_e32 v26, v2
	v_mov_b32_e32 v27, v2
	v_mov_b32_e32 v28, v2
	v_mov_b32_e32 v29, v2
	v_mov_b32_e32 v30, v2
	v_mov_b32_e32 v31, v2
	v_mov_b32_e32 v32, v2
	v_mov_b32_e32 v33, v2
	v_mov_b32_e32 v42, v2
	v_mov_b32_e32 v43, v2
	v_mov_b32_e32 v44, v2
	v_mov_b32_e32 v45, v2
	v_mov_b32_e32 v46, v2
	v_mov_b32_e32 v47, v2
	v_mov_b32_e32 v48, v2
	v_mov_b32_e32 v49, v2
	v_mov_b32_e32 v18, v2
	v_mov_b32_e32 v19, v2
	v_mov_b32_e32 v20, v2
	v_mov_b32_e32 v21, v2
	v_mov_b32_e32 v22, v2
	v_mov_b32_e32 v23, v2
	v_mov_b32_e32 v24, v2
	v_mov_b32_e32 v25, v2
	v_mov_b32_e32 v34, v2
	v_mov_b32_e32 v35, v2
	v_mov_b32_e32 v36, v2
	v_mov_b32_e32 v37, v2
	v_mov_b32_e32 v38, v2
	v_mov_b32_e32 v39, v2
	v_mov_b32_e32 v40, v2
	v_mov_b32_e32 v41, v2
	v_mov_b32_e32 v50, v2
	v_mov_b32_e32 v51, v2
	v_mov_b32_e32 v52, v2
	v_mov_b32_e32 v53, v2
	v_mov_b32_e32 v54, v2
	v_mov_b32_e32 v55, v2
	v_mov_b32_e32 v56, v2
	v_mov_b32_e32 v57, v2
	v_mov_b32_e32 v58, v2
	v_mov_b32_e32 v59, v2
	v_mov_b32_e32 v60, v2
	v_mov_b32_e32 v61, v2
	v_mov_b32_e32 v62, v2
	v_mov_b32_e32 v63, v2
	v_mov_b32_e32 v64, v2
	v_mov_b32_e32 v65, v2
	v_mov_b32_e32 v66, v2
	v_mov_b32_e32 v67, v2
	v_mov_b32_e32 v68, v2
	v_mov_b32_e32 v69, v2
	v_mov_b32_e32 v70, v2
	v_mov_b32_e32 v71, v2
	v_mov_b32_e32 v72, v2
	v_mov_b32_e32 v73, v2
	v_mov_b32_e32 v74, v2
	v_mov_b32_e32 v75, v2
	v_mov_b32_e32 v76, v2
	v_mov_b32_e32 v77, v2
	v_mov_b32_e32 v78, v2
	v_mov_b32_e32 v79, v2
	v_mov_b32_e32 v80, v2
	v_mov_b32_e32 v81, v2
	v_mov_b32_e32 v90, v2
	v_mov_b32_e32 v91, v2
	v_mov_b32_e32 v92, v2
	v_mov_b32_e32 v93, v2
	v_mov_b32_e32 v94, v2
	v_mov_b32_e32 v95, v2
	v_mov_b32_e32 v96, v2
	v_mov_b32_e32 v97, v2
	v_mov_b32_e32 v106, v2
	v_mov_b32_e32 v107, v2
	v_mov_b32_e32 v108, v2
	v_mov_b32_e32 v109, v2
	v_mov_b32_e32 v110, v2
	v_mov_b32_e32 v111, v2
	v_mov_b32_e32 v112, v2
	v_mov_b32_e32 v113, v2
	v_mov_b32_e32 v82, v2
	v_mov_b32_e32 v83, v2
	v_mov_b32_e32 v84, v2
	v_mov_b32_e32 v85, v2
	v_mov_b32_e32 v86, v2
	v_mov_b32_e32 v87, v2
	v_mov_b32_e32 v88, v2
	v_mov_b32_e32 v89, v2
	v_mov_b32_e32 v98, v2
	v_mov_b32_e32 v99, v2
	v_mov_b32_e32 v100, v2
	v_mov_b32_e32 v101, v2
	v_mov_b32_e32 v102, v2
	v_mov_b32_e32 v103, v2
	v_mov_b32_e32 v104, v2
	v_mov_b32_e32 v105, v2
	v_mov_b32_e32 v114, v2
	v_mov_b32_e32 v115, v2
	v_mov_b32_e32 v116, v2
	v_mov_b32_e32 v117, v2
	v_mov_b32_e32 v118, v2
	v_mov_b32_e32 v119, v2
	v_mov_b32_e32 v120, v2
	v_mov_b32_e32 v121, v2
	v_mov_b32_e32 v122, v2
	v_mov_b32_e32 v123, v2
	v_mov_b32_e32 v124, v2
	v_mov_b32_e32 v125, v2
	v_mov_b32_e32 v126, v2
	v_mov_b32_e32 v127, v2
	v_mov_b32_e32 v128, v2
	v_mov_b32_e32 v129, v2
	s_cmp_eq_u32 s58, 2
	s_cbranch_scc0 .LBB0_344
	s_cmp_lt_i32 s88, 0
	s_cbranch_scc0 .LBB0_344
	s_cmp_lt_i32 s55, 32
	s_cbranch_scc1 .LBB0_344
	v_and_b32_e32 v238, 7, v188
	v_or_b32_e32 v238, s86, v238
	v_lshlrev_b32_e32 v238, 13, v238
	v_lshl_add_u32 v238, v225, 2, v238
	v_and_b32_e32 v239, 8, v188
	v_lshl_add_u32 v238, v239, 3, v238
	v_add_u32_e32 v239, 0x10000, v238
	s_lshl_b32 s98, s54, 21
	s_lshl_b32 s99, s23, 10
	s_add_u32 s98, s98, s99
	s_add_u32 s100, s18, s98
	s_addc_u32 s101, s19, 0
	s_branch .Lrk_344
